# + conv sample-row split-K partial loads batched
# speedup vs baseline: 1.0128x; 1.0081x over previous
; __device__ __forceinline__ void phase_conv(KArgs a, int tid) {
;     ...
;     for (int s = blockIdx.x; s < MSAMP; s += gridDim.x) {
;         const int row = MPROMPT + s;
;         const float* SS = (const float*)(a->ws + WS_SS); const float* PS = (const float*)(a->ws + WS_PS); float sq = 0.f;
;         for (int j = 0; j < 32; ++j) sq += SS[(size_t)j * MPAD + row];
;         const float rs = 1.0f / sqrtf(sq * (1.0f / 2048.0f) + RMS_EPS);
;         f32x4 gy = zero, x3 = zero;
; #pragma unroll
;         for (int sl = 0; sl < 8; ++sl) { const float* p = PS + ((size_t)sl * 128 + s) * 4096 + c; gy = gy + *(const f32x4*)p; x3 = x3 + *(const f32x4*)(p + 2048); }
.LBB0_1396:
	s_add_i32 s10, s8, 0x2000
	s_ashr_i32 s11, s10, 31
	s_lshl_b64 s[4:5], s[10:11], 2
	s_add_u32 s4, s2, s4
	s_addc_u32 s5, s12, s5
	global_load_dword v0, v1, s[4:5]
	v_mov_b32_e32 v97, 0x8000
	global_load_dword v97, v97, s[4:5] offset:1024
	v_mov_b32_e32 v98, 0x10000
	global_load_dword v98, v98, s[4:5] offset:2048
	v_mov_b32_e32 v99, 0x18000
	global_load_dword v99, v99, s[4:5] offset:3072
	v_mov_b32_e32 v100, 0x21000
	global_load_dword v100, v100, s[4:5]
	v_mov_b32_e32 v101, 0x29000
	global_load_dword v101, v101, s[4:5] offset:1024
	v_mov_b32_e32 v102, 0x31000
	global_load_dword v102, v102, s[4:5] offset:2048
	v_mov_b32_e32 v103, 0x39000
	global_load_dword v103, v103, s[4:5] offset:3072
	v_mov_b32_e32 v104, 0x42000
	global_load_dword v104, v104, s[4:5]
	v_mov_b32_e32 v105, 0x4a000
	global_load_dword v105, v105, s[4:5] offset:1024
	v_mov_b32_e32 v106, 0x52000
	global_load_dword v106, v106, s[4:5] offset:2048
	v_mov_b32_e32 v107, 0x5a000
	global_load_dword v107, v107, s[4:5] offset:3072
	v_mov_b32_e32 v108, 0x63000
	global_load_dword v108, v108, s[4:5]
	v_mov_b32_e32 v109, 0x6b000
	global_load_dword v109, v109, s[4:5] offset:1024
	v_mov_b32_e32 v110, 0x73000
	global_load_dword v110, v110, s[4:5] offset:2048
	v_mov_b32_e32 v111, 0x7b000
	global_load_dword v111, v111, s[4:5] offset:3072
	v_mov_b32_e32 v112, 0x84000
	global_load_dword v112, v112, s[4:5]
	v_mov_b32_e32 v113, 0x8c000
	global_load_dword v113, v113, s[4:5] offset:1024
	v_mov_b32_e32 v114, 0x94000
	global_load_dword v114, v114, s[4:5] offset:2048
	v_mov_b32_e32 v115, 0x9c000
	global_load_dword v115, v115, s[4:5] offset:3072
	v_mov_b32_e32 v116, 0xa5000
	global_load_dword v116, v116, s[4:5]
	v_mov_b32_e32 v117, 0xad000
	global_load_dword v117, v117, s[4:5] offset:1024
	v_mov_b32_e32 v118, 0xb5000
	global_load_dword v118, v118, s[4:5] offset:2048
	v_mov_b32_e32 v119, 0xbd000
	global_load_dword v119, v119, s[4:5] offset:3072
	v_mov_b32_e32 v120, 0xc6000
	global_load_dword v120, v120, s[4:5]
	v_mov_b32_e32 v121, 0xce000
	global_load_dword v121, v121, s[4:5] offset:1024
	v_mov_b32_e32 v122, 0xd6000
	global_load_dword v122, v122, s[4:5] offset:2048
	v_mov_b32_e32 v123, 0xde000
	global_load_dword v123, v123, s[4:5] offset:3072
	v_mov_b32_e32 v124, 0xe7000
	global_load_dword v124, v124, s[4:5]
	v_mov_b32_e32 v125, 0xef000
	global_load_dword v125, v125, s[4:5] offset:1024
	v_mov_b32_e32 v126, 0xf7000
	global_load_dword v126, v126, s[4:5] offset:2048
	v_mov_b32_e32 v127, 0xff000
	global_load_dword v127, v127, s[4:5] offset:3072
	s_ashr_i32 s9, s8, 31
	s_waitcnt vmcnt(0)
	v_add_f32_e32 v0, 0, v0
	v_add_f32_e32 v0, v0, v97
	v_add_f32_e32 v0, v0, v98
	v_add_f32_e32 v0, v0, v99
	v_add_f32_e32 v0, v0, v100
	v_add_f32_e32 v0, v0, v101
	v_add_f32_e32 v0, v0, v102
	v_add_f32_e32 v0, v0, v103
	v_add_f32_e32 v0, v0, v104
	v_add_f32_e32 v0, v0, v105
	v_add_f32_e32 v0, v0, v106
	v_add_f32_e32 v0, v0, v107
	v_add_f32_e32 v0, v0, v108
	v_add_f32_e32 v0, v0, v109
	v_add_f32_e32 v0, v0, v110
	v_add_f32_e32 v0, v0, v111
	v_add_f32_e32 v0, v0, v112
	v_add_f32_e32 v0, v0, v113
	v_add_f32_e32 v0, v0, v114
	v_add_f32_e32 v0, v0, v115
	v_add_f32_e32 v0, v0, v116
	v_add_f32_e32 v0, v0, v117
	v_add_f32_e32 v0, v0, v118
	v_add_f32_e32 v0, v0, v119
	v_add_f32_e32 v0, v0, v120
	v_add_f32_e32 v0, v0, v121
	v_add_f32_e32 v0, v0, v122
	v_add_f32_e32 v0, v0, v123
	v_add_f32_e32 v0, v0, v124
	v_add_f32_e32 v0, v0, v125
	v_add_f32_e32 v0, v0, v126
	v_add_f32_e32 v0, v0, v127
	v_fmamk_f32 v0, v0, 0x3a000000, v220
	v_cmp_gt_f32_e32 vcc, s43, v0
	v_mul_f32_e32 v24, 0x4f800000, v0
	s_nop 0
	v_cndmask_b32_e32 v0, v0, v24, vcc
	v_sqrt_f32_e32 v24, v0
	s_nop 0
	v_add_u32_e32 v25, -1, v24
	v_fma_f32 v26, -v25, v24, v0
	v_cmp_ge_f32_e64 s[4:5], 0, v26
	v_add_u32_e32 v26, 1, v24
	s_nop 0
	v_cndmask_b32_e64 v25, v24, v25, s[4:5]
	v_fma_f32 v24, -v26, v24, v0
	v_cmp_lt_f32_e64 s[4:5], 0, v24
	s_nop 1
	v_cndmask_b32_e64 v24, v25, v26, s[4:5]
	v_mul_f32_e32 v25, 0x37800000, v24
	s_lshl_b64 s[4:5], s[8:9], 14
	v_cndmask_b32_e32 v24, v24, v25, vcc
	v_cmp_class_f32_e32 vcc, v0, v221
	v_lshl_add_u64 v[66:67], v[38:39], 0, s[4:5]
	s_mov_b32 s4, 0x202000
	v_cndmask_b32_e32 v0, v24, v0, vcc
	global_load_dwordx4 v[96:99], v[66:67], off
	v_add_co_u32_e32 v24, vcc, s38, v66
	s_nop 0
	s_nop 1
	v_addc_co_u32_e32 v25, vcc, 0, v67, vcc
	v_add_co_u32_e32 v28, vcc, s39, v66
	global_load_dwordx4 v[100:103], v[24:25], off
	s_nop 0
	v_addc_co_u32_e32 v29, vcc, 0, v67, vcc
	global_load_dwordx4 v[104:107], v[28:29], off
	v_add_co_u32_e32 v28, vcc, s4, v66
	s_nop 0
	s_nop 1
	v_addc_co_u32_e32 v29, vcc, 0, v67, vcc
	v_add_co_u32_e32 v32, vcc, s77, v66
	global_load_dwordx4 v[108:111], v[28:29], off
	s_nop 0
	v_addc_co_u32_e32 v33, vcc, 0, v67, vcc
	global_load_dwordx4 v[112:115], v[32:33], off
	s_mov_b32 s4, 0x402000
	v_add_co_u32_e32 v32, vcc, s4, v66
	s_nop 0
	s_nop 1
	v_addc_co_u32_e32 v33, vcc, 0, v67, vcc
	v_add_co_u32_e32 v46, vcc, s74, v66
	global_load_dwordx4 v[116:119], v[32:33], off
	s_nop 0
	v_addc_co_u32_e32 v47, vcc, 0, v67, vcc
	global_load_dwordx4 v[120:123], v[46:47], off
	s_mov_b32 s4, 0x602000
	v_add_co_u32_e32 v46, vcc, s4, v66
	s_nop 0
	s_nop 1
	v_addc_co_u32_e32 v47, vcc, 0, v67, vcc
	v_add_co_u32_e32 v50, vcc, s37, v66
	global_load_dwordx4 v[124:127], v[46:47], off
	s_nop 0
	v_addc_co_u32_e32 v51, vcc, 0, v67, vcc
	global_load_dwordx4 v[128:131], v[50:51], off
	s_mov_b32 s4, 0x802000
	v_mad_i64_i32 v[46:47], s[14:15], s8, v231, v[2:3]
	v_add_co_u32_e32 v50, vcc, s4, v66
	s_nop 0
	s_nop 1
	v_addc_co_u32_e32 v51, vcc, 0, v67, vcc
	v_add_co_u32_e32 v54, vcc, s97, v66
	global_load_dwordx4 v[132:135], v[50:51], off
	s_nop 0
	v_addc_co_u32_e32 v55, vcc, 0, v67, vcc
	global_load_dwordx4 v[136:139], v[54:55], off
	s_mov_b32 s4, 0xa02000
	v_add_co_u32_e32 v54, vcc, s4, v66
	s_nop 0
	s_nop 1
	v_addc_co_u32_e32 v55, vcc, 0, v67, vcc
	v_add_co_u32_e32 v58, vcc, s56, v66
	global_load_dwordx4 v[140:143], v[54:55], off
	s_nop 0
	v_addc_co_u32_e32 v59, vcc, 0, v67, vcc
	global_load_dwordx4 v[144:147], v[58:59], off
	s_mov_b32 s4, 0xc02000
	v_add_co_u32_e32 v58, vcc, s4, v66
	s_nop 0
	s_nop 1
	v_addc_co_u32_e32 v59, vcc, 0, v67, vcc
	v_add_co_u32_e32 v62, vcc, s57, v66
	global_load_dwordx4 v[148:151], v[58:59], off
	s_nop 0
	v_addc_co_u32_e32 v63, vcc, 0, v67, vcc
	global_load_dwordx4 v[152:155], v[62:63], off
	s_waitcnt vmcnt(0)
; __device__ __forceinline__ float gelu_tanh_f(float x) { const float t = 1.5957691216f * (x + 0.044715f * x * x * x); return x * fast_rcp(1.0f + __expf(-t)); }
; __device__ __forceinline__ unsigned cvtpk(float lo, float hi) { unsigned r; asm volatile("v_cvt_pk_bf16_f32 %0, %1, %2" : "=v"(r) : "v"(lo), "v"(hi)); return r; }
; __device__ __forceinline__ void phase_conv(KArgs a, int tid) {
;     ...
;         for (int sl = 0; sl < 8; ++sl) { const float* p = PS + ((size_t)sl * 128 + s) * 4096 + c; gy = gy + *(const f32x4*)p; x3 = x3 + *(const f32x4*)(p + 2048); }
;         x3 = x3 * rs; gy = gy * rs;
; #pragma unroll
;         for (int e = 0; e < 4; ++e) gy[e] = pg8::gelu_tanh_f(gy[e]);
;         u32x2 go; go.x = cvtpk(gy[0], gy[1]); go.y = cvtpk(gy[2], gy[3]); *(u32x2*)((bf16*)(a->ws + WS_GATE) + (size_t)row * DM + c) = go;
;         const float* b = buf + (size_t)s * 3 * DM + c;
;         const f32x4 x0 = *(const f32x4*)b, x1 = *(const f32x4*)(b + DM), x2 = *(const f32x4*)(b + 2 * DM);
;         float* o = a->out + OUT_SC + (size_t)s * 3 * DM + c; *(f32x4*)o = x1; *(f32x4*)(o + DM) = x2; *(f32x4*)(o + 2 * DM) = x3;
;         const f32x4 xc = bias + x0 * w0 + x1 * w1 + x2 * w2 + x3 * w3;
;         u32x2 ow; ow.x = cvtpk(xc[0], xc[1]); ow.y = cvtpk(xc[2], xc[3]);
;         *(u32x2*)(XCB + ((size_t)(c >> 8) * MPAD + row) * 256 + (c & 255)) = ow;
	v_pk_add_f32 v[176:177], v[96:97], 0 op_sel_hi:[1,0]
	v_pk_add_f32 v[96:97], v[98:99], 0 op_sel_hi:[1,0]
	v_pk_add_f32 v[98:99], v[100:101], 0 op_sel_hi:[1,0]
	v_pk_add_f32 v[100:101], v[102:103], 0 op_sel_hi:[1,0]
	v_pk_add_f32 v[102:103], v[176:177], v[104:105]
	v_pk_add_f32 v[176:177], v[96:97], v[106:107]
	v_pk_add_f32 v[106:107], v[98:99], v[108:109]
	v_pk_add_f32 v[104:105], v[100:101], v[110:111]
	v_pk_add_f32 v[100:101], v[102:103], v[112:113]
	v_pk_add_f32 v[112:113], v[176:177], v[114:115]
	v_pk_add_f32 v[176:177], v[106:107], v[116:117]
	v_pk_add_f32 v[114:115], v[104:105], v[118:119]
	v_pk_add_f32 v[106:107], v[100:101], v[120:121]
	v_pk_add_f32 v[120:121], v[112:113], v[122:123]
	v_pk_add_f32 v[122:123], v[176:177], v[124:125]
	v_pk_add_f32 v[176:177], v[106:107], v[128:129]
	v_pk_add_f32 v[128:129], v[120:121], v[130:131]
	v_pk_add_f32 v[130:131], v[114:115], v[126:127]
	v_pk_add_f32 v[124:125], v[122:123], v[132:133]
	v_pk_add_f32 v[122:123], v[130:131], v[134:135]
	v_pk_add_f32 v[130:131], v[176:177], v[136:137]
	v_pk_add_f32 v[176:177], v[128:129], v[138:139]
	v_pk_add_f32 v[138:139], v[122:123], v[142:143]
	v_pk_add_f32 v[136:137], v[124:125], v[140:141]
	v_pk_add_f32 v[128:129], v[130:131], v[144:145]
	v_pk_add_f32 v[144:145], v[176:177], v[146:147]
	v_pk_add_f32 v[176:177], v[138:139], v[150:151]
	v_pk_add_f32 v[146:147], v[136:137], v[148:149]
	v_pk_add_f32 v[138:139], v[128:129], v[152:153]
	v_mov_b32_e32 v24, v146
	v_mov_b32_e32 v25, v147
	v_mov_b32_e32 v26, v176
	v_mov_b32_e32 v27, v177
	v_mov_b32_e32 v28, v108
	v_mov_b32_e32 v29, v109
	v_mov_b32_e32 v30, v110
	v_mov_b32_e32 v31, v111
	v_mov_b32_e32 v32, v116
	v_mov_b32_e32 v33, v117
	v_mov_b32_e32 v34, v118
	v_mov_b32_e32 v35, v119
	v_mov_b32_e32 v48, v126
	v_mov_b32_e32 v49, v127
	v_mov_b32_e32 v50, v132
	v_mov_b32_e32 v51, v133
	v_mov_b32_e32 v52, v134
	v_mov_b32_e32 v53, v135
	v_mov_b32_e32 v54, v140
	v_mov_b32_e32 v55, v141
	v_mov_b32_e32 v56, v142
	v_mov_b32_e32 v57, v143
	v_mov_b32_e32 v58, v148
	v_mov_b32_e32 v59, v149
	v_mov_b32_e32 v60, v150
	v_mov_b32_e32 v61, v151
	v_mov_b32_e32 v62, v152
	v_mov_b32_e32 v63, v153
	v_mov_b32_e32 v64, v154
	v_mov_b32_e32 v65, v155
	v_mov_b32_e32 v68, v144
	v_mov_b32_e32 v69, v145
	v_mov_b32_e32 v70, v138
	v_mov_b32_e32 v71, v139
	v_add_co_u32_e32 v62, vcc, 0xe02000, v66
	v_div_scale_f32 v66, s[4:5], v0, v0, 1.0
	s_nop 0
	v_addc_co_u32_e32 v63, vcc, 0, v67, vcc
	v_rcp_f32_e32 v67, v66
	v_pk_add_f32 v[68:69], v[68:69], v[64:65]
	s_lshl_b64 s[4:5], s[10:11], 12
	v_lshl_add_u64 v[30:31], v[40:41], 0, s[4:5]
	v_fma_f32 v72, -v66, v67, 1.0
	v_fmac_f32_e32 v67, v72, v67
	v_div_scale_f32 v72, vcc, 1.0, v0, 1.0
	v_mul_f32_e32 v73, v72, v67
	v_fma_f32 v74, -v66, v73, v72
	v_fmac_f32_e32 v73, v74, v67
	v_fma_f32 v66, -v66, v73, v72
	v_div_fmas_f32 v66, v66, v67, v73
	v_div_fixup_f32 v0, v66, v0, 1.0
	v_pk_mul_f32 v[66:67], v[0:1], v[68:69] op_sel_hi:[0,1]
	v_pk_mul_f32 v[68:69], v[0:1], v[70:71] op_sel_hi:[0,1]
	v_mul_f32_e32 v70, 0x3d372713, v68
	v_mul_f32_e32 v70, v68, v70
	v_fma_f32 v70, v68, v70, v68
	v_mul_f32_e32 v70, 0xbfcc422a, v70
	v_mul_f32_e32 v70, 0x3fb8aa3b, v70
	v_exp_f32_e32 v70, v70
	v_add_co_u32_e32 v32, vcc, s38, v46
	global_load_dwordx4 v[62:65], v[62:63], off
	v_add_f32_e32 v70, 1.0, v70
	v_rcp_f32_e32 v70, v70
	v_addc_co_u32_e32 v33, vcc, 0, v47, vcc
	s_mul_i32 s5, s8, 0x6000
	v_mul_f32_e32 v68, v68, v70
	v_mul_f32_e32 v70, 0x3d372713, v69
	v_mul_f32_e32 v70, v69, v70
	v_fma_f32 v70, v69, v70, v69
	v_mul_f32_e32 v70, 0xbfcc422a, v70
	v_mul_f32_e32 v70, 0x3fb8aa3b, v70
	v_exp_f32_e32 v70, v70
	s_mul_hi_i32 s4, s8, 0x6000
	v_add_f32_e32 v70, 1.0, v70
	v_rcp_f32_e32 v70, v70
	s_waitcnt vmcnt(0)
	v_pk_add_f32 v[26:27], v[26:27], v[64:65]
	v_mul_f32_e32 v69, v69, v70
	v_mul_f32_e32 v70, 0x3d372713, v66
	v_mul_f32_e32 v70, v66, v70
	v_fma_f32 v70, v66, v70, v66
	v_mul_f32_e32 v70, 0xbfcc422a, v70
	v_mul_f32_e32 v70, 0x3fb8aa3b, v70
	v_exp_f32_e32 v70, v70
	v_cvt_pk_bf16_f32 v28, v68, v69
	v_pk_add_f32 v[24:25], v[24:25], v[62:63]
	v_pk_mul_f32 v[26:27], v[0:1], v[26:27] op_sel_hi:[0,1]
	v_add_f32_e32 v70, 1.0, v70
	v_rcp_f32_e32 v70, v70
	v_pk_mul_f32 v[24:25], v[0:1], v[24:25] op_sel_hi:[0,1]
	v_mul_f32_e32 v66, v66, v70
	v_mul_f32_e32 v70, 0x3d372713, v67
	v_mul_f32_e32 v70, v67, v70
	v_fma_f32 v70, v67, v70, v67
	v_mul_f32_e32 v70, 0xbfcc422a, v70
	v_mul_f32_e32 v70, 0x3fb8aa3b, v70
	v_exp_f32_e32 v70, v70
	s_nop 0
	v_add_f32_e32 v70, 1.0, v70
	v_rcp_f32_e32 v70, v70
	s_nop 0
	v_mul_f32_e32 v67, v67, v70
	v_cvt_pk_bf16_f32 v29, v66, v67
	global_store_dwordx2 v[30:31], v[28:29], off
	global_load_dwordx4 v[28:31], v[46:47], off
	s_load_dwordx2 s[14:15], s[6:7], 0x110
	global_load_dwordx4 v[32:35], v[32:33], off
	v_add_co_u32_e32 v46, vcc, s41, v46
	s_waitcnt lgkmcnt(0)
	s_add_u32 s14, s14, s5
	v_addc_co_u32_e32 v47, vcc, 0, v47, vcc
	global_load_dwordx4 v[46:49], v[46:47], off
	s_addc_u32 s15, s15, s4
	v_lshl_add_u64 v[50:51], v[36:37], 2, s[14:15]
	s_mov_b32 s4, 0x4a20000
	v_add_co_u32_e32 v52, vcc, s4, v50
	s_mov_b32 s4, 0x4a22000
	s_nop 0
	v_addc_co_u32_e32 v53, vcc, 0, v51, vcc
	s_add_i32 s8, s8, s73
	s_cmpk_lt_i32 s8, 0x80
	s_waitcnt vmcnt(2)
	v_pk_fma_f32 v[30:31], v[6:7], v[30:31], v[22:23]
	v_pk_fma_f32 v[28:29], v[4:5], v[28:29], v[20:21]
	s_waitcnt vmcnt(1)
	global_store_dwordx4 v[52:53], v[32:35], off
	v_add_co_u32_e32 v52, vcc, s4, v50
	s_mov_b32 s4, 0x4a24000
	s_nop 0
	v_addc_co_u32_e32 v53, vcc, 0, v51, vcc
	v_add_co_u32_e32 v50, vcc, s4, v50
	v_pk_fma_f32 v[30:31], v[10:11], v[34:35], v[30:31]
	v_pk_fma_f32 v[28:29], v[8:9], v[32:33], v[28:29]
	v_addc_co_u32_e32 v51, vcc, 0, v51, vcc
	s_waitcnt vmcnt(1)
	v_pk_fma_f32 v[30:31], v[14:15], v[48:49], v[30:31]
	v_pk_fma_f32 v[28:29], v[12:13], v[46:47], v[28:29]
	global_store_dwordx4 v[50:51], v[24:27], off
	global_store_dwordx4 v[52:53], v[46:49], off
	s_nop 0
	v_pk_fma_f32 v[26:27], v[18:19], v[26:27], v[30:31]
	v_pk_fma_f32 v[24:25], v[16:17], v[24:25], v[28:29]
	s_nop 0
	v_cvt_pk_bf16_f32 v24, v24, v25
	v_cvt_pk_bf16_f32 v25, v26, v27
	v_lshl_add_u64 v[26:27], v[42:43], 0, s[10:11]
	v_lshlrev_b64 v[26:27], 9, v[26:27]
	v_lshl_add_u64 v[26:27], v[44:45], 0, v[26:27]
	global_store_dwordx2 v[26:27], v[24:25], off
	s_cbranch_scc1 .LBB0_1396
